# position-projection dot loops: 8 strided loads per iteration issued together (was load-wait-fma per element)
# speedup vs baseline: 1.0168x; 1.0013x over previous
; DI int TID() { int t = threadIdx.x; asm volatile("" : "+v"(t)); return t; }
; DI void p0_item(const Params& p, int l, int it, const float* __restrict__ xin, char* lds) {
;     ...
;       const int j = it - 4576, kv = j >> 5, kc = j & 31;
;       const int tid = TID(), n = tid & 127, kh = tid >> 7;
;       const float* w1 = (kv ? p.cmp_v_w1 : p.cmp_k_w1) + (size_t)l * 2048 * 128;
;       const float* pos = p.cmp_pos + l * 2048;
;       float a = 0.f;
; #pragma unroll 8
;       for (int k = kc * 64 + kh * 32; k < kc * 64 + kh * 32 + 32; ++k) a += pos[k] * w1[(size_t)k * 128 + n];
;       float* tmp = (float*)lds;
;       tmp[tid] = a;
;       __syncthreads();
;       if (tid < 128) POSP(l)[(size_t)(kv * 32 + kc) * 128 + tid] = tmp[tid] + tmp[tid + 128];
;       __syncthreads();
.LBB0_114:
	global_load_dwordx4 v[10:13], v[4:5], off offset:-12
	global_load_dwordx4 v[14:17], v[4:5], off offset:-28
	global_load_dword v228, v[6:7], off offset:-2048
	global_load_dword v229, v[6:7], off offset:-1536
	global_load_dword v230, v[6:7], off offset:-1024
	global_load_dword v231, v[6:7], off offset:-512
	global_load_dword v232, v[6:7], off
	global_load_dword v233, v[6:7], off offset:512
	global_load_dword v234, v[6:7], off offset:1024
	global_load_dword v235, v[6:7], off offset:1536
	v_add_u32_e32 v3, 8, v3
	v_cmp_ge_i32_e32 vcc, v3, v0
	v_lshl_add_u64 v[4:5], v[4:5], 0, 32
	s_or_b64 s[0:1], vcc, s[0:1]
	v_lshl_add_u64 v[6:7], v[6:7], 0, s[34:35]
	s_waitcnt vmcnt(0)
	v_fmac_f32_e32 v8, v14, v228
	v_fmac_f32_e32 v8, v15, v229
	v_fmac_f32_e32 v8, v16, v230
	v_fmac_f32_e32 v8, v17, v231
	v_fmac_f32_e32 v8, v10, v232
	v_fmac_f32_e32 v8, v11, v233
	v_fmac_f32_e32 v8, v12, v234
	v_fmac_f32_e32 v8, v13, v235
	s_andn2_b64 exec, exec, s[0:1]
	s_cbranch_execnz .LBB0_114
	s_or_b64 exec, exec, s[0:1]
	s_movk_i32 s0, 0x80
	v_lshlrev_b32_e32 v0, 2, v2
	v_cmp_gt_i32_e32 vcc, s0, v2
	ds_write_b32 v0, v8
	s_waitcnt lgkmcnt(0)
	s_barrier
	s_and_saveexec_b64 s[0:1], vcc
	s_cbranch_execz .LBB0_117
	ds_read2st64_b32 v[4:5], v0 offset1:2
	v_readlane_b32 s8, v251, 34
	s_lshl_b64 s[2:3], s[6:7], 9
	v_readlane_b32 s22, v251, 48
	v_readlane_b32 s23, v251, 49
	s_add_u32 s2, s22, s2
	s_addc_u32 s3, s23, s3
	v_ashrrev_i32_e32 v3, 31, v2
	v_lshl_add_u64 v[2:3], v[2:3], 2, s[2:3]
	s_waitcnt lgkmcnt(0)
	v_add_f32_e32 v0, v4, v5
	v_readlane_b32 s9, v251, 35
	v_readlane_b32 s10, v251, 36
	v_readlane_b32 s11, v251, 37
	v_readlane_b32 s12, v251, 38
	v_readlane_b32 s13, v251, 39
	v_readlane_b32 s14, v251, 40
	v_readlane_b32 s15, v251, 41
	v_readlane_b32 s16, v251, 42
	v_readlane_b32 s17, v251, 43
	v_readlane_b32 s18, v251, 44
	v_readlane_b32 s19, v251, 45
	v_readlane_b32 s20, v251, 46
	v_readlane_b32 s21, v251, 47
	global_store_dword v[2:3], v0, off

; DI int TID() { int t = threadIdx.x; asm volatile("" : "+v"(t)); return t; }
; DI void p0_item(const Params& p, int l, int it, const float* __restrict__ xin, char* lds) {
;     ...
;       const int j = it - 4576, kv = j >> 5, kc = j & 31;
;       const int tid = TID(), n = tid & 127, kh = tid >> 7;
;       const float* w1 = (kv ? p.cmp_v_w1 : p.cmp_k_w1) + (size_t)l * 2048 * 128;
;       const float* pos = p.cmp_pos + l * 2048;
;       float a = 0.f;
; #pragma unroll 8
;       for (int k = kc * 64 + kh * 32; k < kc * 64 + kh * 32 + 32; ++k) a += pos[k] * w1[(size_t)k * 128 + n];
;       float* tmp = (float*)lds;
;       tmp[tid] = a;
;       __syncthreads();
;       if (tid < 128) POSP(l)[(size_t)(kv * 32 + kc) * 128 + tid] = tmp[tid] + tmp[tid + 128];
;       __syncthreads();
.LBB0_526:
	global_load_dwordx4 v[10:13], v[6:7], off offset:-12
	global_load_dwordx4 v[14:17], v[6:7], off offset:-28
	global_load_dword v228, v[4:5], off offset:-3584
	global_load_dword v229, v[4:5], off offset:-3072
	global_load_dword v230, v[4:5], off offset:-2560
	global_load_dword v231, v[4:5], off offset:-2048
	global_load_dword v232, v[4:5], off offset:-1536
	global_load_dword v233, v[4:5], off offset:-1024
	global_load_dword v234, v[4:5], off offset:-512
	global_load_dword v235, v[4:5], off
	v_add_u32_e32 v3, 8, v3
	v_cmp_ge_i32_e32 vcc, v3, v0
	v_lshl_add_u64 v[6:7], v[6:7], 0, 32
	s_or_b64 s[0:1], vcc, s[0:1]
	v_lshl_add_u64 v[4:5], v[4:5], 0, s[34:35]
	s_waitcnt vmcnt(0)
	v_fmac_f32_e32 v8, v14, v228
	v_fmac_f32_e32 v8, v15, v229
	v_fmac_f32_e32 v8, v16, v230
	v_fmac_f32_e32 v8, v17, v231
	v_fmac_f32_e32 v8, v10, v232
	v_fmac_f32_e32 v8, v11, v233
	v_fmac_f32_e32 v8, v12, v234
	v_fmac_f32_e32 v8, v13, v235
	s_andn2_b64 exec, exec, s[0:1]
	s_cbranch_execnz .LBB0_526
	s_or_b64 exec, exec, s[0:1]
	s_movk_i32 s0, 0x80
	v_lshlrev_b32_e32 v0, 2, v2
	v_cmp_gt_i32_e32 vcc, s0, v2
	ds_write_b32 v0, v8
	s_waitcnt lgkmcnt(0)
	s_barrier
	s_and_saveexec_b64 s[0:1], vcc
	s_mov_b64 s[18:19], s[6:7]
	s_cbranch_execz .LBB0_529
	ds_read2st64_b32 v[4:5], v0 offset1:2
	s_lshl_b64 s[2:3], s[18:19], 9
	v_readlane_b32 s5, v252, 63
	s_add_u32 s2, s5, s2
	v_readlane_b32 s5, v253, 0
	s_addc_u32 s3, s5, s3
	v_ashrrev_i32_e32 v3, 31, v2
	v_lshl_add_u64 v[2:3], v[2:3], 2, s[2:3]
	s_waitcnt lgkmcnt(0)
	v_add_f32_e32 v0, v4, v5
	global_store_dword v[2:3], v0, off
